# best5 + ssm2 pass-2 carry-in: serial per-chunk load->wait->FMA loop replaced by rounds of up to 6 load pairs in flight (same math order)
# baseline (speedup 1.0000x reference)
; template <bool PASS2> __device__ __forceinline__ void ssm2_pass(const Ctx& c, int l) {
;     ...
;         if (PASS2 && tk > 0) {
;             float pAr = arA, pAi = aiA, pBr = arB, pBi = aiB;
; #pragma unroll
;             for (int k = 0; k < 8; ++k) { float nr = pAr * pAr - pAi * pAi, ni = 2.f * pAr * pAi; pAr = nr; pAi = ni; nr = pBr * pBr - pBi * pBi; ni = 2.f * pBr * pBi; pBr = nr; pBi = ni; }
;             for (int j = 0; j < tk; ++j) { const float2 eA = *(const float2*)(send + ((size_t)(bg * 16 + j) * 64 + q) * 2), eB = *(const float2*)(send + ((size_t)(bg * 16 + j) * 64 + 32 + q) * 2);
;                 float nr = pAr * xAr - pAi * xAi + eA.x, ni = pAr * xAi + pAi * xAr + eA.y; xAr = nr; xAi = ni;
;                 nr = pBr * xBr - pBi * xBi + eB.x; ni = pBr * xBi + pBi * xBr + eB.y; xBr = nr; xBi = ni; }
;         }
.LBB0_120:
.Lcarry_round:
	global_load_dwordx2 v[184:185], v[70:71], off
	global_load_dwordx2 v[186:187], v[70:71], off offset:256
	s_cmp_lt_u32 s34, 2
	s_cbranch_scc1 .Lcarry_issued
	global_load_dwordx2 v[188:189], v[70:71], off offset:512
	global_load_dwordx2 v[190:191], v[70:71], off offset:768
	s_cmp_lt_u32 s34, 3
	s_cbranch_scc1 .Lcarry_issued
	global_load_dwordx2 v[192:193], v[70:71], off offset:1024
	global_load_dwordx2 v[204:205], v[70:71], off offset:1280
	s_cmp_lt_u32 s34, 4
	s_cbranch_scc1 .Lcarry_issued
	global_load_dwordx2 v[206:207], v[70:71], off offset:1536
	global_load_dwordx2 v[234:235], v[70:71], off offset:1792
	s_cmp_lt_u32 s34, 5
	s_cbranch_scc1 .Lcarry_issued
	global_load_dwordx2 v[238:239], v[70:71], off offset:2048
	global_load_dwordx2 v[240:241], v[70:71], off offset:2304
	s_cmp_lt_u32 s34, 6
	s_cbranch_scc1 .Lcarry_issued
	global_load_dwordx2 v[242:243], v[70:71], off offset:2560
	global_load_dwordx2 v[244:245], v[70:71], off offset:2816
.Lcarry_issued:
	s_waitcnt vmcnt(0)
	v_pk_mul_f32 v[80:81], v[74:75], v[168:169]
	v_pk_mul_f32 v[82:83], v[72:73], v[168:169]
	v_pk_fma_f32 v[80:81], v[72:73], v[166:167], v[80:81] neg_lo:[0,0,1] neg_hi:[0,0,1]
	v_pk_fma_f32 v[82:83], v[74:75], v[166:167], v[82:83]
	v_add_f32_e32 v166, v80, v184
	v_add_f32_e32 v167, v81, v186
	v_add_f32_e32 v168, v82, v185
	v_add_f32_e32 v169, v83, v187
	s_cmp_lt_u32 s34, 2
	s_cbranch_scc1 .Lcarry_done
	v_pk_mul_f32 v[80:81], v[74:75], v[168:169]
	v_pk_mul_f32 v[82:83], v[72:73], v[168:169]
	v_pk_fma_f32 v[80:81], v[72:73], v[166:167], v[80:81] neg_lo:[0,0,1] neg_hi:[0,0,1]
	v_pk_fma_f32 v[82:83], v[74:75], v[166:167], v[82:83]
	v_add_f32_e32 v166, v80, v188
	v_add_f32_e32 v167, v81, v190
	v_add_f32_e32 v168, v82, v189
	v_add_f32_e32 v169, v83, v191
	s_cmp_lt_u32 s34, 3
	s_cbranch_scc1 .Lcarry_done
	v_pk_mul_f32 v[80:81], v[74:75], v[168:169]
	v_pk_mul_f32 v[82:83], v[72:73], v[168:169]
	v_pk_fma_f32 v[80:81], v[72:73], v[166:167], v[80:81] neg_lo:[0,0,1] neg_hi:[0,0,1]
	v_pk_fma_f32 v[82:83], v[74:75], v[166:167], v[82:83]
	v_add_f32_e32 v166, v80, v192
	v_add_f32_e32 v167, v81, v204
	v_add_f32_e32 v168, v82, v193
	v_add_f32_e32 v169, v83, v205
	s_cmp_lt_u32 s34, 4
	s_cbranch_scc1 .Lcarry_done
	v_pk_mul_f32 v[80:81], v[74:75], v[168:169]
	v_pk_mul_f32 v[82:83], v[72:73], v[168:169]
	v_pk_fma_f32 v[80:81], v[72:73], v[166:167], v[80:81] neg_lo:[0,0,1] neg_hi:[0,0,1]
	v_pk_fma_f32 v[82:83], v[74:75], v[166:167], v[82:83]
	v_add_f32_e32 v166, v80, v206
	v_add_f32_e32 v167, v81, v234
	v_add_f32_e32 v168, v82, v207
	v_add_f32_e32 v169, v83, v235
	s_cmp_lt_u32 s34, 5
	s_cbranch_scc1 .Lcarry_done
	v_pk_mul_f32 v[80:81], v[74:75], v[168:169]
	v_pk_mul_f32 v[82:83], v[72:73], v[168:169]
	v_pk_fma_f32 v[80:81], v[72:73], v[166:167], v[80:81] neg_lo:[0,0,1] neg_hi:[0,0,1]
	v_pk_fma_f32 v[82:83], v[74:75], v[166:167], v[82:83]
	v_add_f32_e32 v166, v80, v238
	v_add_f32_e32 v167, v81, v240
	v_add_f32_e32 v168, v82, v239
	v_add_f32_e32 v169, v83, v241
	s_cmp_lt_u32 s34, 6
	s_cbranch_scc1 .Lcarry_done
	v_pk_mul_f32 v[80:81], v[74:75], v[168:169]
	v_pk_mul_f32 v[82:83], v[72:73], v[168:169]
	v_pk_fma_f32 v[80:81], v[72:73], v[166:167], v[80:81] neg_lo:[0,0,1] neg_hi:[0,0,1]
	v_pk_fma_f32 v[82:83], v[74:75], v[166:167], v[82:83]
	v_add_f32_e32 v166, v80, v242
	v_add_f32_e32 v167, v81, v244
	v_add_f32_e32 v168, v82, v243
	v_add_f32_e32 v169, v83, v245
	s_cmp_lt_u32 s34, 7
	s_cbranch_scc1 .Lcarry_done
	s_add_i32 s34, s34, -6
	s_mov_b64 s[42:43], 0xc00
	v_lshl_add_u64 v[70:71], v[70:71], 0, s[42:43]
	s_branch .Lcarry_round
.Lcarry_done:
	s_mov_b32 s34, 0
	s_branch .LBB0_123
